# attention: next unit's Q rows and first two K/V tiles requested before this unit's tail and result stores (counted wait leaves the stores outstanding) + 4 dwordx4 result stores per lane
# speedup vs baseline: 1.0048x; 1.0048x over previous
.LBB0_447:
	s_or_b64 exec, exec, s[0:1]
	s_mov_b64 s[0:1], s[86:87]
	s_waitcnt lgkmcnt(0)
	s_barrier
	s_load_dwordx2 s[0:1], s[86:87], 0xa8
	s_mov_b32 s15, m0
	v_and_b32_e32 v1, 63, v0
	v_and_b32_e32 v2, 31, v0
	v_bfe_u32 v3, v0, 5, 1
	v_readfirstlane_b32 s18, v0
	v_mov_b32_e32 v15, 0x7f7f7f7f
	s_nop 3
	s_lshr_b32 s18, s18, 6
	s_lshl_b32 s14, s18, 10
	v_lshrrev_b32_e32 v13, 2, v1
	s_and_b32 s19, s18, 3
	s_lshl_b32 s19, s19, 4
	v_add_u32_e32 v13, s19, v13
	v_mul_u32_u24_e32 v4, 0xc0, v13
	v_lshrrev_b32_e32 v14, 4, v1
	v_xor_b32_e32 v14, v14, v1
	v_and_b32_e32 v14, 3, v14
	v_lshlrev_b32_e32 v14, 4, v14
	s_lshr_b32 s20, s18, 2
	s_lshl_b32 s20, s20, 6
	v_add3_u32 v4, v4, v14, s20
	v_add_u32_e32 v247, 0x40, v4
	v_add_u32_e32 v5, 0x80, v4
	v_lshrrev_b32_e32 v13, 2, v1
	s_lshl_b32 s19, s18, 4
	v_add_u32_e32 v13, s19, v13
	v_mul_u32_u24_e32 v13, 0x2000, v13
	v_add_u32_e32 v6, v13, v14
	v_bfe_u32 v13, v2, 2, 1
	v_lshlrev_b32_e32 v13, 5, v13
	v_and_b32_e32 v14, 3, v2
	v_add_u32_e32 v13, v13, v14
	v_lshrrev_b32_e32 v14, 3, v2
	v_lshl_add_u32 v13, v14, 2, v13
	v_lshlrev_b32_e32 v13, 6, v13
	v_lshlrev_b32_e32 v246, 1, v3
	v_xor_b32_e32 v246, v246, v14
	v_lshl_add_u32 v7, v246, 4, v13
	v_xor_b32_e32 v8, 16, v7
	v_bfe_u32 v13, v2, 2, 2
	v_lshlrev_b32_e32 v14, 1, v3
	v_xor_b32_e32 v13, v13, v14
	v_lshlrev_b32_e32 v13, 4, v13
	v_lshl_add_u32 v9, v2, 6, v13
	v_add_u32_e32 v9, 0xc000, v9
	v_xor_b32_e32 v10, 16, v9
	s_lshl_b32 s19, s18, 5
	v_add_u32_e32 v13, s19, v2
	v_mul_u32_u24_e32 v240, 0xc00, v13
	v_lshl_add_u32 v240, v3, 5, v240
	v_lshlrev_b32_e32 v241, 11, v13
	v_lshl_add_u32 v241, v3, 6, v241
	s_mov_b32 s12, 0
	s_waitcnt lgkmcnt(0)
	s_mov_b32 s33, 0
.Latt_unit:
	s_cmp_eq_u32 s33, 1
	s_cbranch_scc1 .Latt_warm
	s_cmp_eq_u32 s3, 0x100
	s_cbranch_scc0 .Latt_gen
	s_lshl_b32 s19, s12, 3
	s_cmp_ge_u32 s19, 48
	s_cbranch_scc1 .Latt_done
	s_and_b32 s20, s2, 7
	s_or_b32 s19, s19, s20
	s_lshr_b32 s20, s2, 3
	s_branch .Latt_have

.Latt_have:
	s_lshr_b32 s21, s19, 4
	s_and_b32 s33, s19, 15
	s_lshl_b32 s21, s21, 13
	s_lshl_b32 s34, s20, 8
	s_add_u32 s21, s21, s34
	s_mul_i32 s34, s21, 0xc00
	s_mul_i32 s35, s33, 0xc0
	s_add_u32 s34, s34, s35
	s_add_u32 s34, s34, 0x5000000
	s_add_u32 s4, s0, s34
	s_addc_u32 s5, s1, 0
	s_mul_i32 s34, s19, 0x180000
	s_add_u32 s34, s34, 0x3a400000
	s_add_u32 s6, s0, s34
	s_addc_u32 s7, s1, 0
	s_mul_i32 s34, s19, 0x100000
	s_add_u32 s34, s34, 0x13400000
	s_add_u32 s8, s0, s34
	s_addc_u32 s9, s1, 0
	s_lshl_b32 s34, s21, 11
	s_lshl_b32 s35, s33, 7
	s_add_u32 s34, s34, s35
	s_add_u32 s34, s34, 0x4c400000
	s_add_u32 s10, s0, s34
	s_addc_u32 s11, s1, 0
	s_mov_b32 s33, 0
	global_load_dwordx4 v[128:131], v240, s[4:5] offset:0
	global_load_dwordx4 v[132:135], v240, s[4:5] offset:16
	global_load_dwordx4 v[136:139], v240, s[4:5] offset:64
	global_load_dwordx4 v[140:143], v240, s[4:5] offset:80
	global_load_dwordx4 v[144:147], v240, s[4:5] offset:128
	global_load_dwordx4 v[148:151], v240, s[4:5] offset:144
	s_cmp_lt_u32 s18, 4
	s_cbranch_scc0 .Latt_pro_b
	s_mov_b32 s19, 0
	s_mul_i32 s20, s19, 0x3000
	s_add_i32 s20, s20, s14
	s_mov_b32 m0, s20
	s_lshl_b32 s21, s19, 13
	global_load_lds_dwordx4 v4, s[6:7]
	s_add_i32 s20, s20, 0x2000
	s_mov_b32 m0, s20
	s_nop 0
	global_load_lds_dwordx4 v5, s[6:7]
	s_add_i32 s21, s21, s14
	s_add_i32 s21, s21, 0xc000
	s_mov_b32 m0, s21
	s_add_u32 s6, s6, 0x3000
	s_addc_u32 s7, s7, 0
	global_load_lds_dwordx4 v6, s[8:9]
	s_add_u32 s8, s8, 64
	s_addc_u32 s9, s9, 0
	s_mov_b32 s19, 1
	s_mul_i32 s20, s19, 0x3000
	s_add_i32 s20, s20, s14
	s_mov_b32 m0, s20
	s_lshl_b32 s21, s19, 13
	global_load_lds_dwordx4 v4, s[6:7]
	s_add_i32 s20, s20, 0x2000
	s_mov_b32 m0, s20
	s_nop 0
	global_load_lds_dwordx4 v5, s[6:7]
	s_add_i32 s21, s21, s14
	s_add_i32 s21, s21, 0xc000
	s_mov_b32 m0, s21
	s_add_u32 s6, s6, 0x3000
	s_addc_u32 s7, s7, 0
	global_load_lds_dwordx4 v6, s[8:9]
	s_add_u32 s8, s8, 64
	s_addc_u32 s9, s9, 0
	s_branch .Latt_pro_done
.Latt_pro_b:
	s_mov_b32 s19, 0
	s_mul_i32 s20, s19, 0x3000
	s_add_i32 s20, s20, s14
	s_mov_b32 m0, s20
	s_lshl_b32 s21, s19, 13
	global_load_lds_dwordx4 v4, s[6:7]
	s_add_i32 s21, s21, s14
	s_add_i32 s21, s21, 0xc000
	s_mov_b32 m0, s21
	s_add_u32 s6, s6, 0x3000
	s_addc_u32 s7, s7, 0
	global_load_lds_dwordx4 v6, s[8:9]
	s_add_u32 s8, s8, 64
	s_addc_u32 s9, s9, 0
	s_mov_b32 s19, 1
	s_mul_i32 s20, s19, 0x3000
	s_add_i32 s20, s20, s14
	s_mov_b32 m0, s20
	s_lshl_b32 s21, s19, 13
	global_load_lds_dwordx4 v4, s[6:7]
	s_add_i32 s21, s21, s14
	s_add_i32 s21, s21, 0xc000
	s_mov_b32 m0, s21
	s_add_u32 s6, s6, 0x3000
	s_addc_u32 s7, s7, 0
	global_load_lds_dwordx4 v6, s[8:9]
	s_add_u32 s8, s8, 64
	s_addc_u32 s9, s9, 0
	s_branch .Latt_pro_done
.Latt_warm:
	s_mov_b32 s10, s34
	s_mov_b32 s11, s35
.Latt_pro_done:
	v_mov_b32_e32 v64, 0
	v_mov_b32_e32 v65, 0
	v_mov_b32_e32 v66, 0
	v_mov_b32_e32 v67, 0
	v_mov_b32_e32 v68, 0
	v_mov_b32_e32 v69, 0
	v_mov_b32_e32 v70, 0
	v_mov_b32_e32 v71, 0
	v_mov_b32_e32 v72, 0
	v_mov_b32_e32 v73, 0
	v_mov_b32_e32 v74, 0
	v_mov_b32_e32 v75, 0
	v_mov_b32_e32 v76, 0
	v_mov_b32_e32 v77, 0
	v_mov_b32_e32 v78, 0
	v_mov_b32_e32 v79, 0
	v_mov_b32_e32 v80, 0
	v_mov_b32_e32 v81, 0
	v_mov_b32_e32 v82, 0
	v_mov_b32_e32 v83, 0
	v_mov_b32_e32 v84, 0
	v_mov_b32_e32 v85, 0
	v_mov_b32_e32 v86, 0
	v_mov_b32_e32 v87, 0
	v_mov_b32_e32 v88, 0
	v_mov_b32_e32 v89, 0
	v_mov_b32_e32 v90, 0
	v_mov_b32_e32 v91, 0
	v_mov_b32_e32 v92, 0
	v_mov_b32_e32 v93, 0
	v_mov_b32_e32 v94, 0
	v_mov_b32_e32 v95, 0
	v_mov_b32_e32 v96, 0
	v_mov_b32_e32 v97, 0
	v_mov_b32_e32 v98, 0
	v_mov_b32_e32 v99, 0
	v_mov_b32_e32 v100, 0
	v_mov_b32_e32 v101, 0
	v_mov_b32_e32 v102, 0
	v_mov_b32_e32 v103, 0
	v_mov_b32_e32 v104, 0
	v_mov_b32_e32 v105, 0
	v_mov_b32_e32 v106, 0
	v_mov_b32_e32 v107, 0
	v_mov_b32_e32 v108, 0
	v_mov_b32_e32 v109, 0
	v_mov_b32_e32 v110, 0
	v_mov_b32_e32 v111, 0
	v_mov_b32_e32 v112, 0
	v_mov_b32_e32 v113, 0
	v_mov_b32_e32 v114, 0
	v_mov_b32_e32 v115, 0
	v_mov_b32_e32 v116, 0
	v_mov_b32_e32 v117, 0
	v_mov_b32_e32 v118, 0
	v_mov_b32_e32 v119, 0
	v_mov_b32_e32 v120, 0
	v_mov_b32_e32 v121, 0
	v_mov_b32_e32 v122, 0
	v_mov_b32_e32 v123, 0
	v_mov_b32_e32 v124, 0
	v_mov_b32_e32 v125, 0
	v_mov_b32_e32 v126, 0
	v_mov_b32_e32 v127, 0
	v_mov_b32_e32 v16, 0
	v_mov_b32_e32 v17, 0
	v_mov_b32_e32 v18, 0
	v_mov_b32_e32 v19, 0
	v_mov_b32_e32 v20, 0
	v_mov_b32_e32 v21, 0
	v_mov_b32_e32 v22, 0
	v_mov_b32_e32 v23, 0
	v_mov_b32_e32 v24, 0
	v_mov_b32_e32 v25, 0
	v_mov_b32_e32 v26, 0
	v_mov_b32_e32 v27, 0
	v_mov_b32_e32 v28, 0
	v_mov_b32_e32 v29, 0
	v_mov_b32_e32 v30, 0
	v_mov_b32_e32 v31, 0
	v_mov_b32_e32 v11, 0
	s_mov_b32 s16, 0xbf800000
	s_mov_b32 s17, 0xff800000
	s_mov_b32 s13, 0
	s_cmp_eq_u32 s33, 1
	s_mov_b32 s33, 0
	s_cbranch_scc0 .Latt_coldwait
	s_waitcnt vmcnt(4)
	s_branch .Latt_waited

.Latt_waited:
	s_cmp_lt_u32 s18, 4
	s_cbranch_scc0 .Latt_b_entry
	v_mov_b32_e32 v200, 0
	v_mov_b32_e32 v201, 0
	v_mov_b32_e32 v202, 0
	v_mov_b32_e32 v203, 0
	v_mov_b32_e32 v204, 0
	v_mov_b32_e32 v205, 0
	v_mov_b32_e32 v206, 0
	v_mov_b32_e32 v207, 0
	v_mov_b32_e32 v208, 0
	v_mov_b32_e32 v209, 0
	v_mov_b32_e32 v210, 0
	v_mov_b32_e32 v211, 0
	v_mov_b32_e32 v212, 0
	v_mov_b32_e32 v213, 0
	v_mov_b32_e32 v214, 0
	v_mov_b32_e32 v215, 0
	v_mov_b32_e32 v216, 0
	v_mov_b32_e32 v217, 0
	v_mov_b32_e32 v218, 0
	v_mov_b32_e32 v219, 0
	v_mov_b32_e32 v220, 0
	v_mov_b32_e32 v221, 0
	v_mov_b32_e32 v222, 0
	v_mov_b32_e32 v223, 0
	v_mov_b32_e32 v224, 0
	v_mov_b32_e32 v225, 0
	v_mov_b32_e32 v226, 0
	v_mov_b32_e32 v227, 0
	v_mov_b32_e32 v228, 0
	v_mov_b32_e32 v229, 0
	v_mov_b32_e32 v230, 0
	v_mov_b32_e32 v231, 0
	v_mov_b32_e32 v232, 0
	v_mov_b32_e32 v233, 0
	v_mov_b32_e32 v234, 0
	v_mov_b32_e32 v235, 0
	v_mov_b32_e32 v236, 0
	v_mov_b32_e32 v237, 0
	v_mov_b32_e32 v238, 0
	v_mov_b32_e32 v239, 0

.Latt_pack_a:
	v_cvt_pk_fp8_f32 v232, v32, v33
	v_cvt_pk_fp8_f32 v233, v36, v37
	v_cvt_pk_fp8_f32 v234, v40, v41
	v_cvt_pk_fp8_f32 v235, v44, v45
	v_cvt_pk_fp8_f32 v236, v48, v49
	v_cvt_pk_fp8_f32 v237, v52, v53
	v_cvt_pk_fp8_f32 v238, v56, v57
	v_cvt_pk_fp8_f32 v239, v60, v61
	v_cvt_pk_fp8_f32 v232, v34, v35 op_sel:[0,0,1]
	v_cvt_pk_fp8_f32 v233, v38, v39 op_sel:[0,0,1]
	v_cvt_pk_fp8_f32 v234, v42, v43 op_sel:[0,0,1]
	v_cvt_pk_fp8_f32 v235, v46, v47 op_sel:[0,0,1]
	v_cvt_pk_fp8_f32 v236, v50, v51 op_sel:[0,0,1]
	v_cvt_pk_fp8_f32 v237, v54, v55 op_sel:[0,0,1]
	v_cvt_pk_fp8_f32 v238, v58, v59 op_sel:[0,0,1]
	v_cvt_pk_fp8_f32 v239, v62, v63 op_sel:[0,0,1]
	s_add_u32 s13, s13, 1
	s_cmp_lt_u32 s13, 128
	s_cbranch_scc1 .Latt_a_loop
	s_add_u32 s35, s12, 1
	s_cmp_eq_u32 s3, 0x100
	s_cbranch_scc0 .Latt_gen_na
	s_lshl_b32 s19, s35, 3
	s_cmp_ge_u32 s19, 48
	s_cbranch_scc1 .Latt_nonext_na
	s_and_b32 s20, s2, 7
	s_or_b32 s19, s19, s20
	s_lshr_b32 s20, s2, 3
	s_branch .Latt_have_na
.Latt_gen_na:
	s_mul_i32 s19, s35, s3
	s_add_u32 s19, s19, s2
	s_cmp_ge_u32 s19, 0x600
	s_cbranch_scc1 .Latt_nonext_na
	s_and_b32 s20, s19, 31
	s_lshr_b32 s19, s19, 5
.Latt_have_na:
	s_lshr_b32 s21, s19, 4
	s_and_b32 s33, s19, 15
	s_lshl_b32 s21, s21, 13
	s_lshl_b32 s34, s20, 8
	s_add_u32 s21, s21, s34
	s_mul_i32 s34, s21, 0xc00
	s_mul_i32 s35, s33, 0xc0
	s_add_u32 s34, s34, s35
	s_add_u32 s34, s34, 0x5000000
	s_add_u32 s4, s0, s34
	s_addc_u32 s5, s1, 0
	s_mul_i32 s34, s19, 0x180000
	s_add_u32 s34, s34, 0x3a400000
	s_add_u32 s6, s0, s34
	s_addc_u32 s7, s1, 0
	s_mul_i32 s34, s19, 0x100000
	s_add_u32 s34, s34, 0x13400000
	s_add_u32 s8, s0, s34
	s_addc_u32 s9, s1, 0
	s_lshl_b32 s34, s21, 11
	s_lshl_b32 s35, s33, 7
	s_add_u32 s34, s34, s35
	s_add_u32 s34, s34, 0x4c400000
	s_add_u32 s34, s0, s34
	s_addc_u32 s35, s1, 0
	global_load_dwordx4 v[128:131], v240, s[4:5] offset:0
	global_load_dwordx4 v[132:135], v240, s[4:5] offset:16
	global_load_dwordx4 v[136:139], v240, s[4:5] offset:64
	global_load_dwordx4 v[140:143], v240, s[4:5] offset:80
	global_load_dwordx4 v[144:147], v240, s[4:5] offset:128
	global_load_dwordx4 v[148:151], v240, s[4:5] offset:144
	s_mov_b32 s19, 0
	s_mul_i32 s20, s19, 0x3000
	s_add_i32 s20, s20, s14
	s_mov_b32 m0, s20
	s_lshl_b32 s21, s19, 13
	global_load_lds_dwordx4 v4, s[6:7]
	s_add_i32 s20, s20, 0x2000
	s_mov_b32 m0, s20
	s_nop 0
	global_load_lds_dwordx4 v5, s[6:7]
	s_add_i32 s21, s21, s14
	s_add_i32 s21, s21, 0xc000
	s_mov_b32 m0, s21
	s_add_u32 s6, s6, 0x3000
	s_addc_u32 s7, s7, 0
	global_load_lds_dwordx4 v6, s[8:9]
	s_add_u32 s8, s8, 64
	s_addc_u32 s9, s9, 0
	s_mov_b32 s19, 1
	s_mul_i32 s20, s19, 0x3000
	s_add_i32 s20, s20, s14
	s_mov_b32 m0, s20
	s_lshl_b32 s21, s19, 13
	global_load_lds_dwordx4 v4, s[6:7]
	s_add_i32 s20, s20, 0x2000
	s_mov_b32 m0, s20
	s_nop 0
	global_load_lds_dwordx4 v5, s[6:7]
	s_add_i32 s21, s21, s14
	s_add_i32 s21, s21, 0xc000
	s_mov_b32 m0, s21
	s_add_u32 s6, s6, 0x3000
	s_addc_u32 s7, s7, 0
	global_load_lds_dwordx4 v6, s[8:9]
	s_add_u32 s8, s8, 64
	s_addc_u32 s9, s9, 0
	s_mov_b32 s33, 1
.Latt_nonext_na:
	s_waitcnt lgkmcnt(0)
	v_mfma_f32_32x32x64_f8f6f4 v[64:79], v[200:207], v[232:239], v[64:79]
	v_mfma_f32_32x32x64_f8f6f4 v[80:95], v[208:215], v[232:239], v[80:95]
	v_mfma_f32_32x32x64_f8f6f4 v[96:111], v[216:223], v[232:239], v[96:111]
	v_mfma_f32_32x32x64_f8f6f4 v[112:127], v[224:231], v[232:239], v[112:127]
	s_branch .Latt_final

.Latt_sk2_b:
	s_waitcnt lgkmcnt(12)
	v_mfma_f32_32x32x64_f8f6f4 v[112:127], v[224:231], v[232:239], v[112:127]
	s_waitcnt lgkmcnt(10)
	v_mfma_f32_32x32x64_f8f6f4 v[32:47], v[152:159], v[128:135], v[16:31]
	s_waitcnt lgkmcnt(8)
	v_mfma_f32_32x32x64_f8f6f4 v[48:63], v[176:183], v[128:135], v[16:31]
	s_waitcnt lgkmcnt(6)
	v_mfma_f32_32x32x64_f8f6f4 v[32:47], v[160:167], v[136:143], v[32:47]
	s_waitcnt lgkmcnt(4)
	v_mfma_f32_32x32x64_f8f6f4 v[48:63], v[184:191], v[136:143], v[48:63]
	s_waitcnt lgkmcnt(2)
	v_mfma_f32_32x32x64_f8f6f4 v[32:47], v[168:175], v[144:151], v[32:47]
	s_waitcnt lgkmcnt(0)
	v_mfma_f32_32x32x64_f8f6f4 v[48:63], v[192:199], v[144:151], v[48:63]
	s_add_u32 s13, s13, 1
	s_cmp_lt_u32 s13, 128
	s_cbranch_scc1 .Latt_b_loop
	s_add_u32 s35, s12, 1
	s_cmp_eq_u32 s3, 0x100
	s_cbranch_scc0 .Latt_gen_nb
	s_lshl_b32 s19, s35, 3
	s_cmp_ge_u32 s19, 48
	s_cbranch_scc1 .Latt_nonext_nb
	s_and_b32 s20, s2, 7
	s_or_b32 s19, s19, s20
	s_lshr_b32 s20, s2, 3
	s_branch .Latt_have_nb

.Latt_have_nb:
	s_lshr_b32 s21, s19, 4
	s_and_b32 s33, s19, 15
	s_lshl_b32 s21, s21, 13
	s_lshl_b32 s34, s20, 8
	s_add_u32 s21, s21, s34
	s_mul_i32 s34, s21, 0xc00
	s_mul_i32 s35, s33, 0xc0
	s_add_u32 s34, s34, s35
	s_add_u32 s34, s34, 0x5000000
	s_add_u32 s4, s0, s34
	s_addc_u32 s5, s1, 0
	s_mul_i32 s34, s19, 0x180000
	s_add_u32 s34, s34, 0x3a400000
	s_add_u32 s6, s0, s34
	s_addc_u32 s7, s1, 0
	s_mul_i32 s34, s19, 0x100000
	s_add_u32 s34, s34, 0x13400000
	s_add_u32 s8, s0, s34
	s_addc_u32 s9, s1, 0
	s_lshl_b32 s34, s21, 11
	s_lshl_b32 s35, s33, 7
	s_add_u32 s34, s34, s35
	s_add_u32 s34, s34, 0x4c400000
	s_add_u32 s34, s0, s34
	s_addc_u32 s35, s1, 0
	global_load_dwordx4 v[128:131], v240, s[4:5] offset:0
	global_load_dwordx4 v[132:135], v240, s[4:5] offset:16
	global_load_dwordx4 v[136:139], v240, s[4:5] offset:64
	global_load_dwordx4 v[140:143], v240, s[4:5] offset:80
	global_load_dwordx4 v[144:147], v240, s[4:5] offset:128
	global_load_dwordx4 v[148:151], v240, s[4:5] offset:144
	s_mov_b32 s19, 0
	s_mul_i32 s20, s19, 0x3000
	s_add_i32 s20, s20, s14
	s_mov_b32 m0, s20
	s_lshl_b32 s21, s19, 13
	global_load_lds_dwordx4 v4, s[6:7]
	s_add_i32 s21, s21, s14
	s_add_i32 s21, s21, 0xc000
	s_mov_b32 m0, s21
	s_add_u32 s6, s6, 0x3000
	s_addc_u32 s7, s7, 0
	global_load_lds_dwordx4 v6, s[8:9]
	s_add_u32 s8, s8, 64
	s_addc_u32 s9, s9, 0
	s_mov_b32 s19, 1
	s_mul_i32 s20, s19, 0x3000
	s_add_i32 s20, s20, s14
	s_mov_b32 m0, s20
	s_lshl_b32 s21, s19, 13
	global_load_lds_dwordx4 v4, s[6:7]
	s_add_i32 s21, s21, s14
	s_add_i32 s21, s21, 0xc000
	s_mov_b32 m0, s21
	s_add_u32 s6, s6, 0x3000
	s_addc_u32 s7, s7, 0
	global_load_lds_dwordx4 v6, s[8:9]
	s_add_u32 s8, s8, 64
	s_addc_u32 s9, s9, 0
	s_mov_b32 s33, 1
.Latt_nonext_nb:
	s_mov_b32 s19, 3
	s_lshl_b32 s21, s19, 13
	v_add_u32_e32 v244, s21, v9
	v_add_u32_e32 v245, s21, v10
	ds_read_b128 v[200:203], v244 offset:0
	ds_read_b128 v[204:207], v245 offset:0
	ds_read_b128 v[208:211], v244 offset:2048
	ds_read_b128 v[212:215], v245 offset:2048
	ds_read_b128 v[216:219], v244 offset:4096
	ds_read_b128 v[220:223], v245 offset:4096
	ds_read_b128 v[224:227], v244 offset:6144
	ds_read_b128 v[228:231], v245 offset:6144
	s_nop 9
	v_exp_f32_e32 v32, v32
	v_exp_f32_e32 v33, v33
	v_exp_f32_e32 v34, v34
	v_exp_f32_e32 v35, v35
	v_exp_f32_e32 v36, v36
	v_exp_f32_e32 v37, v37
	v_exp_f32_e32 v38, v38
	v_exp_f32_e32 v39, v39
	v_add_f32_e32 v12, v32, v33
	v_add_f32_e32 v12, v12, v34
	v_add_f32_e32 v12, v12, v35
	v_exp_f32_e32 v40, v40
	v_exp_f32_e32 v41, v41
	v_exp_f32_e32 v42, v42
	v_exp_f32_e32 v43, v43
	v_add_f32_e32 v12, v12, v36
	v_add_f32_e32 v12, v12, v37
	v_add_f32_e32 v12, v12, v38
	v_add_f32_e32 v12, v12, v39
	v_exp_f32_e32 v44, v44
	v_exp_f32_e32 v45, v45
	v_exp_f32_e32 v46, v46
	v_exp_f32_e32 v47, v47
	v_add_f32_e32 v12, v12, v40
	v_add_f32_e32 v12, v12, v41
	v_add_f32_e32 v12, v12, v42
	v_add_f32_e32 v12, v12, v43
	v_exp_f32_e32 v48, v48
	v_exp_f32_e32 v49, v49
	v_exp_f32_e32 v50, v50
	v_exp_f32_e32 v51, v51
	v_add_f32_e32 v12, v12, v44
	v_add_f32_e32 v12, v12, v45
	v_add_f32_e32 v12, v12, v46
	v_add_f32_e32 v12, v12, v47
	v_exp_f32_e32 v52, v52
	v_exp_f32_e32 v53, v53
	v_exp_f32_e32 v54, v54
	v_exp_f32_e32 v55, v55
	v_add_f32_e32 v13, v48, v49
	v_add_f32_e32 v13, v13, v50
	v_add_f32_e32 v13, v13, v51
	v_exp_f32_e32 v56, v56
	v_exp_f32_e32 v57, v57
	v_exp_f32_e32 v58, v58
	v_exp_f32_e32 v59, v59
	v_add_f32_e32 v13, v13, v52
	v_add_f32_e32 v13, v13, v53
	v_add_f32_e32 v13, v13, v54
	v_add_f32_e32 v13, v13, v55
	v_exp_f32_e32 v60, v60
	v_exp_f32_e32 v61, v61
	v_exp_f32_e32 v62, v62
	v_exp_f32_e32 v63, v63
	v_add_f32_e32 v13, v13, v56
	v_add_f32_e32 v13, v13, v57
	v_add_f32_e32 v13, v13, v58
	v_add_f32_e32 v13, v13, v59
	v_add_f32_e32 v13, v13, v60
	v_add_f32_e32 v13, v13, v61
	v_add_f32_e32 v13, v13, v62
	v_add_f32_e32 v13, v13, v63
	v_add_f32_e32 v12, v12, v13
	v_mov_b32_e32 v14, v12
	s_nop 1
	v_permlane32_swap_b32_e32 v12, v14
	v_add_f32_e32 v12, v12, v14
	v_cmp_nge_f32_e32 vcc, s16, v12
	s_cbranch_vccnz .Latt_rare_bt
	v_add_f32_e32 v11, v11, v12
